# threshold 690 + one static s_setprio 1 for waves 0-3 (older half) during phase 2
# baseline (speedup 1.0000x reference)
.LBB0_405:
	s_or_b64 exec, exec, s[0:1]
	s_abs_i32 s0, s3
	v_cvt_f32_u32_e32 v0, s0
	s_sub_i32 s5, 0, s0
	s_add_i32 s1, s3, 0xd7f
	s_xor_b32 s4, s1, s3
	v_rcp_iflag_f32_e32 v0, v0
	s_abs_i32 s1, s1
	s_ashr_i32 s4, s4, 31
	s_mov_b32 s97, 0
	v_mul_f32_e32 v0, 0x4f7ffffe, v0
	v_cvt_u32_f32_e32 v0, v0
	s_waitcnt lgkmcnt(0)
	s_barrier
	v_readfirstlane_b32 s6, v0
	s_mul_i32 s5, s5, s6
	s_mul_hi_u32 s5, s6, s5
	s_add_i32 s6, s6, s5
	s_mul_hi_u32 s5, s1, s6
	s_mul_i32 s6, s5, s0
	s_sub_i32 s1, s1, s6
	s_add_i32 s7, s5, 1
	s_sub_i32 s6, s1, s0
	s_cmp_ge_u32 s1, s0
	s_cselect_b32 s5, s7, s5
	s_cselect_b32 s1, s6, s1
	s_add_i32 s6, s5, 1
	s_cmp_ge_u32 s1, s0
	s_cselect_b32 s0, s6, s5
	s_xor_b32 s0, s0, s4
	s_sub_i32 s35, s0, s4
	v_cvt_f32_u32_e32 v0, s35
	s_lshr_b32 s0, s2, 3
	v_writelane_b32 v255, s0, 0
	s_cmp_lt_i32 s35, 1
	v_rcp_iflag_f32_e32 v0, v0
	s_nop 0
	v_mul_f32_e32 v0, 0x4f7ffffe, v0
	v_cvt_u32_f32_e32 v0, v0
	s_nop 0
	v_readfirstlane_b32 s0, v0
	s_cbranch_scc1 .LBB0_1041
	s_sub_i32 s1, 0, s35
	s_mul_i32 s1, s1, s0
	s_mul_hi_u32 s1, s0, s1
	s_add_i32 s0, s0, s1
	v_readlane_b32 s1, v255, 0
	s_mul_hi_u32 s0, s1, s0
	s_mul_i32 s0, s0, s35
	s_sub_i32 s0, s1, s0
	s_sub_i32 s1, s0, s35
	s_cmp_ge_u32 s0, s35
	s_cselect_b32 s0, s1, s0
	s_sub_i32 s1, s0, s35
	s_cmp_ge_u32 s0, s35
	s_cselect_b32 s46, s1, s0
	s_mov_b32 s27, 0x800000
	s_movk_i32 s48, 0x80
	v_mov_b32_e32 v137, 0
	s_movk_i32 s53, 0x300
	s_mov_b32 s24, 0x3f317217
	s_mov_b32 s25, 0x7f800000
	s_movk_i32 s49, 0xbf
	s_mov_b32 s26, 0x8f8d000
	s_mov_b32 s50, 0xf149f2ca
	s_movk_i32 s51, 0x47
	s_movk_i32 s52, 0xa0
	s_movk_i32 s47, 0x90
	s_mov_b32 s54, 0xff61b1e6
	v_mov_b32_e32 v195, 16
	v_mov_b32_e32 v211, 0x180
	v_mbcnt_hi_u32_b32 v193, -1, v193
	v_mov_b32_e32 v213, 0x41b17218
	v_mov_b32_e32 v215, 0xf149f2ca
	s_mov_b32 s55, 0
	v_readfirstlane_b32 s98, v192
	s_lshr_b32 s98, s98, 6
	s_cmp_ge_u32 s98, 4
	s_cbranch_scc1 .Lp2prio_done
	s_setprio 1
